# ssd_state: next-unit decay factors computed in the loop latch (vmcnt(14)) instead of behind vmcnt(7)/(6) right after the prefetch loads
# speedup vs baseline: 1.0002x; 1.0002x over previous
.LBB0_309:
	s_or_b64 exec, exec, s[38:39]
	s_waitcnt vmcnt(14)
	v_mul_f32_e32 v142, 0x3fb8aa3b, v142
	v_mul_f32_e32 v143, 0x3fb8aa3b, v143
	v_exp_f32_e32 v142, v142
	v_exp_f32_e32 v143, v143
	s_nop 0
	v_xor_b32_e32 v88, 0x80000000, v142
	v_xor_b32_e32 v89, 0x80000000, v143
	s_andn2_b64 vcc, exec, s[36:37]
	s_mov_b32 s34, s44
	s_mov_b32 s30, s43
	s_cbranch_vccz .LBB0_319

.LBB0_312:
	s_waitcnt lgkmcnt(0)
	s_barrier
	ds_read2_b32 v[62:63], v45 offset0:127 offset1:128
	ds_read_b32 v24, v91
	ds_read_b32 v25, v91 offset:1024
	s_waitcnt vmcnt(12)
	v_lshlrev_b32_e32 v28, 16, v0
	v_and_b32_e32 v29, 0xffff0000, v0
	v_lshlrev_b32_e32 v30, 16, v1
	s_waitcnt lgkmcnt(1)
	v_sub_f32_e32 v24, v62, v24
	v_mul_f32_e32 v24, 0x3fb8aa3b, v24
	v_exp_f32_e32 v24, v24
	v_and_b32_e32 v31, 0xffff0000, v1
	v_lshlrev_b32_e32 v34, 16, v2
	v_and_b32_e32 v35, 0xffff0000, v2
	s_waitcnt lgkmcnt(0)
	v_mul_f32_e32 v32, v25, v24
	v_pk_mul_f32 v[24:25], v[32:33], v[28:29] op_sel_hi:[0,1]
	v_pk_mul_f32 v[26:27], v[32:33], v[30:31] op_sel_hi:[0,1]
	v_lshlrev_b32_e32 v36, 16, v3
	v_and_b32_e32 v37, 0xffff0000, v3
	v_cvt_pk_bf16_f32 v24, v24, v25
	v_cvt_pk_bf16_f32 v25, v26, v27
	v_pk_mul_f32 v[26:27], v[32:33], v[34:35] op_sel_hi:[0,1]
	v_pk_mul_f32 v[32:33], v[32:33], v[36:37] op_sel_hi:[0,1]
	v_cvt_pk_bf16_f32 v26, v26, v27
	v_cvt_pk_bf16_f32 v27, v32, v33
	ds_write_b128 v50, v[24:27] offset:2048
	ds_read_b32 v24, v91 offset:512
	ds_read_b32 v25, v91 offset:1536
	s_add_i32 s40, s40, s94
	s_cmpk_gt_i32 s40, 0xbff
	s_cselect_b64 s[36:37], -1, 0
	s_waitcnt lgkmcnt(1)
	v_sub_f32_e32 v24, v63, v24
	v_mul_f32_e32 v24, 0x3fb8aa3b, v24
	v_exp_f32_e32 v24, v24
	s_and_b64 vcc, exec, s[36:37]
	s_waitcnt lgkmcnt(0)
	v_mul_f32_e32 v32, v25, v24
	v_pk_mul_f32 v[24:25], v[32:33], v[28:29] op_sel_hi:[0,1]
	v_pk_mul_f32 v[26:27], v[32:33], v[30:31] op_sel_hi:[0,1]
	v_cvt_pk_bf16_f32 v24, v24, v25
	v_cvt_pk_bf16_f32 v25, v26, v27
	v_pk_mul_f32 v[26:27], v[32:33], v[34:35] op_sel_hi:[0,1]
	v_pk_mul_f32 v[28:29], v[32:33], v[36:37] op_sel_hi:[0,1]
	v_cvt_pk_bf16_f32 v26, v26, v27
	v_cvt_pk_bf16_f32 v27, v28, v29
	ds_write_b128 v50, v[24:27] offset:20480
	ds_read_b32 v24, v51
	ds_read_b32 v25, v51 offset:1024
	v_lshlrev_b32_e32 v30, 16, v4
	v_and_b32_e32 v31, 0xffff0000, v4
	v_lshlrev_b32_e32 v32, 16, v5
	s_waitcnt lgkmcnt(1)
	v_sub_f32_e32 v24, v62, v24
	v_mul_f32_e32 v24, 0x3fb8aa3b, v24
	v_exp_f32_e32 v24, v24
	v_and_b32_e32 v33, 0xffff0000, v5
	v_lshlrev_b32_e32 v34, 16, v6
	v_and_b32_e32 v35, 0xffff0000, v6
	s_waitcnt lgkmcnt(0)
	v_mul_f32_e32 v28, v25, v24
	v_pk_mul_f32 v[24:25], v[28:29], v[30:31] op_sel_hi:[0,1]
	v_pk_mul_f32 v[26:27], v[28:29], v[32:33] op_sel_hi:[0,1]
	v_lshlrev_b32_e32 v36, 16, v7
	v_and_b32_e32 v37, 0xffff0000, v7
	v_cvt_pk_bf16_f32 v24, v24, v25
	v_cvt_pk_bf16_f32 v25, v26, v27
	v_pk_mul_f32 v[26:27], v[28:29], v[34:35] op_sel_hi:[0,1]
	v_pk_mul_f32 v[28:29], v[28:29], v[36:37] op_sel_hi:[0,1]
	v_cvt_pk_bf16_f32 v26, v26, v27
	v_cvt_pk_bf16_f32 v27, v28, v29
	ds_write_b128 v52, v[24:27] offset:2048
	ds_read_b32 v24, v51 offset:512
	ds_read_b32 v25, v51 offset:1536
	s_waitcnt lgkmcnt(1)
	v_sub_f32_e32 v24, v63, v24
	v_mul_f32_e32 v24, 0x3fb8aa3b, v24
	v_exp_f32_e32 v24, v24
	s_waitcnt lgkmcnt(0)
	v_mul_f32_e32 v28, v25, v24
	v_pk_mul_f32 v[24:25], v[28:29], v[30:31] op_sel_hi:[0,1]
	v_pk_mul_f32 v[26:27], v[28:29], v[32:33] op_sel_hi:[0,1]
	v_cvt_pk_bf16_f32 v24, v24, v25
	v_cvt_pk_bf16_f32 v25, v26, v27
	v_pk_mul_f32 v[26:27], v[28:29], v[34:35] op_sel_hi:[0,1]
	v_pk_mul_f32 v[28:29], v[28:29], v[36:37] op_sel_hi:[0,1]
	v_cvt_pk_bf16_f32 v26, v26, v27
	v_cvt_pk_bf16_f32 v27, v28, v29
	ds_write_b128 v52, v[24:27] offset:20480
	s_waitcnt vmcnt(11)
	ds_write_b128 v96, v[8:11] offset:38912
	s_waitcnt vmcnt(10)
	ds_write_b128 v97, v[12:15] offset:38912
	s_waitcnt vmcnt(9)
	ds_write_b128 v98, v[16:19] offset:38912
	s_waitcnt vmcnt(8)
	ds_write_b128 v99, v[20:23] offset:38912
	s_cbranch_vccnz .LBB0_316
	s_and_b32 s35, s40, 7
	s_lshl_b32 s28, s35, 2
	v_readlane_b32 s44, v253, 0
	v_mov_b32_e32 v0, s28
	v_readlane_b32 s56, v253, 12
	v_readlane_b32 s57, v253, 13
	s_nop 4
	global_load_dword v142, v0, s[56:57]
	global_load_dword v143, v0, s[56:57] offset:32
	v_readlane_b32 s45, v253, 1
	v_readlane_b32 s44, v253, 39
	s_ashr_i32 s38, s40, 3
	v_readlane_b32 s45, v253, 40
	s_and_b64 vcc, exec, s[44:45]
	s_lshl_b32 s31, s38, 7
	v_readlane_b32 s46, v253, 2
	v_readlane_b32 s47, v253, 3
	v_readlane_b32 s48, v253, 4
	v_readlane_b32 s49, v253, 5
	v_readlane_b32 s50, v253, 6
	v_readlane_b32 s51, v253, 7
	v_readlane_b32 s52, v253, 8
	v_readlane_b32 s53, v253, 9
	v_readlane_b32 s54, v253, 10
	v_readlane_b32 s55, v253, 11
	v_readlane_b32 s58, v253, 14
	v_readlane_b32 s59, v253, 15
	s_cbranch_vccnz .LBB0_315
	v_add_u32_e32 v0, s31, v68
	v_ashrrev_i32_e32 v1, 31, v0
	v_readlane_b32 s44, v253, 35
	v_lshlrev_b64 v[0:1], 6, v[0:1]
	v_readlane_b32 s45, v253, 36
	s_nop 1
	v_lshl_add_u64 v[0:1], s[44:45], 0, v[0:1]
	v_lshl_add_u64 v[0:1], v[0:1], 0, s[28:29]
	global_load_dword v40, v[0:1], off
	global_load_dword v42, v[0:1], off offset:32
	global_load_dword v41, v[0:1], off offset:64
	global_load_dword v43, v[0:1], off offset:96
.LBB0_315:
	s_add_i32 s28, s38, 0xffffff00
	s_lshr_b32 s28, s28, 6
	s_add_i32 s28, s28, 8
	s_ashr_i32 s39, s40, 8
	s_cmpk_lt_i32 s38, 0x100
	s_cselect_b32 s28, s39, s28
	s_cselect_b32 s44, 31, 63
	s_lshl_b32 s28, s28, 4
	s_lshl_b32 s39, s35, 1
	s_or_b32 s28, s28, s39
	s_lshl_b32 s45, s28, 6
	s_and_b32 s38, s44, s38
	s_or_b32 s39, s28, 1
	s_lshl_b32 s43, s28, 5
	s_add_i32 s46, s45, 0xfffff000
	s_cmpk_lt_i32 s28, 0x80
	s_cselect_b32 s28, s43, s46
	s_lshl_b32 s43, s39, 5
	s_addk_i32 s45, 0xf040
	s_cmpk_lt_i32 s39, 0x80
	s_cselect_b32 s39, s43, s45
	s_or_b32 s43, s28, s38
	s_lshr_b32 s28, s35, 2
	s_sub_i32 s38, s44, s38
	s_add_i32 s44, s38, s39
	s_mul_i32 s38, s28, 0x1800000
	v_readlane_b32 s46, v253, 41
	v_readlane_b32 s47, v253, 42
	s_add_u32 s38, s46, s38
	s_addc_u32 s39, s47, 0
	s_lshl_b32 s35, s35, 7
	s_and_b32 s35, s35, 0x180
	s_add_u32 s38, s38, s35
	v_add_u32_e32 v2, s31, v69
	v_add_u32_e32 v4, s31, v70
	v_add_u32_e32 v8, s31, v71
	v_add_u32_e32 v10, s31, v72
	v_add_u32_e32 v18, s31, v73
	v_add_u32_e32 v20, s31, v74
	s_addc_u32 s39, s39, 0
	v_ashrrev_i32_e32 v3, 31, v2
	v_ashrrev_i32_e32 v5, 31, v4
	s_lshl_b32 s28, s28, 8
	v_ashrrev_i32_e32 v9, 31, v8
	v_ashrrev_i32_e32 v11, 31, v10
	v_ashrrev_i32_e32 v19, 31, v18
	v_ashrrev_i32_e32 v21, 31, v20
	v_lshl_add_u64 v[0:1], s[38:39], 0, v[44:45]
	v_lshlrev_b64 v[2:3], 9, v[2:3]
	v_lshlrev_b64 v[4:5], 9, v[4:5]
	v_lshl_add_u64 v[16:17], v[46:47], 0, s[28:29]
	v_lshlrev_b64 v[8:9], 9, v[8:9]
	v_lshlrev_b64 v[10:11], 9, v[10:11]
	v_lshlrev_b64 v[18:19], 9, v[18:19]
	v_lshlrev_b64 v[20:21], 9, v[20:21]
	v_lshl_add_u64 v[2:3], v[0:1], 0, v[2:3]
	v_lshl_add_u64 v[4:5], v[0:1], 0, v[4:5]
	v_lshl_add_u64 v[8:9], v[16:17], 0, v[8:9]
	v_lshl_add_u64 v[12:13], v[16:17], 0, v[10:11]
	v_lshl_add_u64 v[18:19], v[16:17], 0, v[18:19]
	v_lshl_add_u64 v[20:21], v[16:17], 0, v[20:21]
	global_load_dwordx4 v[0:3], v[2:3], off
	s_nop 0
	global_load_dwordx4 v[4:7], v[4:5], off
	s_nop 0
	global_load_dwordx4 v[8:11], v[8:9], off
	s_nop 0
	global_load_dwordx4 v[12:15], v[12:13], off
	s_nop 0
	global_load_dwordx4 v[16:19], v[18:19], off
	s_nop 0
	global_load_dwordx4 v[20:23], v[20:21], off
	s_branch .LBB0_317
